# gate/up epilogue: row-scale cache fill loads batched 3 rows at a time (3 round trips instead of 8)
# speedup vs baseline: 1.0040x; 1.0020x over previous
; #define LAS __attribute__((address_space(3)))
; #define EPI_ROWS _Pragma("unroll") for (int ai = 0; ai < 2; ++ai) _Pragma("unroll") for (int m = 0; m < 4; ++m)
; DI float sum16(const float* p) { const f32x4* q = (const f32x4*)p; f32x4 a = q[0], b = q[1], c = q[2], d = q[3]; return ((a[0] + a[1]) + (a[2] + a[3])) + ((b[0] + b[1]) + (b[2] + b[3])) + ((c[0] + c[1]) + (c[2] + c[3])) + ((d[0] + d[1]) + (d[2] + d[3])); }
;     DI void operator()(AccRef acc, const Unit& u, int wr, int wc, int fr, int fq) const {
;     ...
;         LAS float* rc_ = (LAS float*)(lds + LDS_RC + (wr * 4 + wc) * 2048) + (fq * 16 + fr);
;         if (u.pm != cpm) { EPI_ROWS { const size_t row = EPI_ROW; rc_[(ai * 4 + m) * 64] = rsqrtf(sum16(XSS + row * 16) * (1.f / 1024.f) + EPS); } cpm = u.pm; }
.LBB0_2127:
	s_lshl_b32 s10, s93, 8
	v_mov_b32_e32 v197, v175
	v_mov_b32_e32 v128, v174
	s_add_i32 s10, s10, s88
	s_cmp_lg_u32 s93, s23
	v_lshlrev_b32_e32 v129, 6, v197
	v_lshlrev_b32_e32 v130, 2, v128
	v_add_u32_e32 v168, s10, v128
	v_add3_u32 v196, s91, v129, v130
	v_ashrrev_i32_e32 v169, 31, v168
	s_mov_b64 s[38:39], -1
	v_add_u32_e32 v166, 16, v168
	v_add_u32_e32 v164, 32, v168
	v_add_u32_e32 v162, 48, v168
	v_add_u32_e32 v160, 0x80, v168
	v_add_u32_e32 v158, 0x90, v168
	v_add_u32_e32 v156, 0xa0, v168
	v_add_u32_e32 v154, 0xb0, v168
	s_cbranch_scc0 .LBB0_2129
	v_ashrrev_i32_e32 v167, 31, v166
	v_ashrrev_i32_e32 v165, 31, v164
	v_ashrrev_i32_e32 v163, 31, v162
	v_ashrrev_i32_e32 v161, 31, v160
	v_ashrrev_i32_e32 v159, 31, v158
	v_ashrrev_i32_e32 v157, 31, v156
	v_ashrrev_i32_e32 v155, 31, v154
	v_lshlrev_b32_e32 v226, 6, v168
	v_lshlrev_b32_e32 v227, 6, v166
	v_lshlrev_b32_e32 v228, 6, v164
	global_load_dwordx4 v[128:131], v226, s[2:3]
	global_load_dwordx4 v[132:135], v226, s[2:3] offset:16
	global_load_dwordx4 v[136:139], v226, s[2:3] offset:32
	global_load_dwordx4 v[140:143], v226, s[2:3] offset:48
	global_load_dwordx4 v[170:173], v227, s[2:3]
	global_load_dwordx4 v[178:181], v227, s[2:3] offset:16
	global_load_dwordx4 v[198:201], v227, s[2:3] offset:32
	global_load_dwordx4 v[206:209], v227, s[2:3] offset:48
	global_load_dwordx4 v[210:213], v228, s[2:3]
	global_load_dwordx4 v[214:217], v228, s[2:3] offset:16
	global_load_dwordx4 v[218:221], v228, s[2:3] offset:32
	global_load_dwordx4 v[222:225], v228, s[2:3] offset:48
	s_waitcnt vmcnt(0)
	v_add_f32_e32 v128, v128, v129
	v_add_f32_e32 v130, v130, v131
	v_add_f32_e32 v132, v132, v133
	v_add_f32_e32 v134, v134, v135
	v_add_f32_e32 v136, v136, v137
	v_add_f32_e32 v138, v138, v139
	v_add_f32_e32 v140, v140, v141
	v_add_f32_e32 v142, v142, v143
	v_add_f32_e32 v128, v128, v130
	v_add_f32_e32 v132, v132, v134
	v_add_f32_e32 v136, v136, v138
	v_add_f32_e32 v140, v140, v142
	v_add_f32_e32 v128, v128, v132
	v_add_f32_e32 v128, v128, v136
	v_add_f32_e32 v128, v128, v140
	v_mul_f32_e32 v128, 0x3a800000, v128
	v_add_f32_e32 v128, 0x358637bd, v128
	v_add_f32_e32 v170, v170, v171
	v_add_f32_e32 v172, v172, v173
	v_add_f32_e32 v178, v178, v179
	v_add_f32_e32 v180, v180, v181
	v_add_f32_e32 v198, v198, v199
	v_add_f32_e32 v200, v200, v201
	v_add_f32_e32 v206, v206, v207
	v_add_f32_e32 v208, v208, v209
	v_add_f32_e32 v170, v170, v172
	v_add_f32_e32 v178, v178, v180
	v_add_f32_e32 v198, v198, v200
	v_add_f32_e32 v206, v206, v208
	v_add_f32_e32 v170, v170, v178
	v_add_f32_e32 v170, v170, v198
	v_add_f32_e32 v170, v170, v206
	v_mul_f32_e32 v170, 0x3a800000, v170
	v_add_f32_e32 v170, 0x358637bd, v170
	v_add_f32_e32 v210, v210, v211
	v_add_f32_e32 v212, v212, v213
	v_add_f32_e32 v214, v214, v215
	v_add_f32_e32 v216, v216, v217
	v_add_f32_e32 v218, v218, v219
	v_add_f32_e32 v220, v220, v221
	v_add_f32_e32 v222, v222, v223
	v_add_f32_e32 v224, v224, v225
	v_add_f32_e32 v210, v210, v212
	v_add_f32_e32 v214, v214, v216
	v_add_f32_e32 v218, v218, v220
	v_add_f32_e32 v222, v222, v224
	v_add_f32_e32 v210, v210, v214
	v_add_f32_e32 v210, v210, v218
	v_add_f32_e32 v210, v210, v222
	v_mul_f32_e32 v210, 0x3a800000, v210
	v_add_f32_e32 v210, 0x358637bd, v210
	v_rsq_f32_e32 v128, v128
	v_rsq_f32_e32 v170, v170
	v_rsq_f32_e32 v210, v210
	s_nop 1
	ds_write_b32 v196, v128
	ds_write_b32 v196, v170 offset:256
	ds_write_b32 v196, v210 offset:512
	v_lshlrev_b32_e32 v226, 6, v162
	v_lshlrev_b32_e32 v227, 6, v160
	v_lshlrev_b32_e32 v228, 6, v158
	global_load_dwordx4 v[128:131], v226, s[2:3]
	global_load_dwordx4 v[132:135], v226, s[2:3] offset:16
	global_load_dwordx4 v[136:139], v226, s[2:3] offset:32
	global_load_dwordx4 v[140:143], v226, s[2:3] offset:48
	global_load_dwordx4 v[170:173], v227, s[2:3]
	global_load_dwordx4 v[178:181], v227, s[2:3] offset:16
	global_load_dwordx4 v[198:201], v227, s[2:3] offset:32
	global_load_dwordx4 v[206:209], v227, s[2:3] offset:48
	global_load_dwordx4 v[210:213], v228, s[2:3]
	global_load_dwordx4 v[214:217], v228, s[2:3] offset:16
	global_load_dwordx4 v[218:221], v228, s[2:3] offset:32
	global_load_dwordx4 v[222:225], v228, s[2:3] offset:48
	s_waitcnt vmcnt(0)
; #define LAS __attribute__((address_space(3)))
; #define EPI_ROWS _Pragma("unroll") for (int ai = 0; ai < 2; ++ai) _Pragma("unroll") for (int m = 0; m < 4; ++m)
; DI float sum16(const float* p) { const f32x4* q = (const f32x4*)p; f32x4 a = q[0], b = q[1], c = q[2], d = q[3]; return ((a[0] + a[1]) + (a[2] + a[3])) + ((b[0] + b[1]) + (b[2] + b[3])) + ((c[0] + c[1]) + (c[2] + c[3])) + ((d[0] + d[1]) + (d[2] + d[3])); }
;     DI void operator()(AccRef acc, const Unit& u, int wr, int wc, int fr, int fq) const {
;     ...
;         LAS float* rc_ = (LAS float*)(lds + LDS_RC + (wr * 4 + wc) * 2048) + (fq * 16 + fr);
;         if (u.pm != cpm) { EPI_ROWS { const size_t row = EPI_ROW; rc_[(ai * 4 + m) * 64] = rsqrtf(sum16(XSS + row * 16) * (1.f / 1024.f) + EPS); } cpm = u.pm; }
	v_add_f32_e32 v128, v128, v129
	v_add_f32_e32 v130, v130, v131
	v_add_f32_e32 v132, v132, v133
	v_add_f32_e32 v134, v134, v135
	v_add_f32_e32 v136, v136, v137
	v_add_f32_e32 v138, v138, v139
	v_add_f32_e32 v140, v140, v141
	v_add_f32_e32 v142, v142, v143
	v_add_f32_e32 v128, v128, v130
	v_add_f32_e32 v132, v132, v134
	v_add_f32_e32 v136, v136, v138
	v_add_f32_e32 v140, v140, v142
	v_add_f32_e32 v128, v128, v132
	v_add_f32_e32 v128, v128, v136
	v_add_f32_e32 v128, v128, v140
	v_mul_f32_e32 v128, 0x3a800000, v128
	v_add_f32_e32 v128, 0x358637bd, v128
	v_add_f32_e32 v170, v170, v171
	v_add_f32_e32 v172, v172, v173
	v_add_f32_e32 v178, v178, v179
	v_add_f32_e32 v180, v180, v181
	v_add_f32_e32 v198, v198, v199
	v_add_f32_e32 v200, v200, v201
	v_add_f32_e32 v206, v206, v207
	v_add_f32_e32 v208, v208, v209
	v_add_f32_e32 v170, v170, v172
	v_add_f32_e32 v178, v178, v180
	v_add_f32_e32 v198, v198, v200
	v_add_f32_e32 v206, v206, v208
	v_add_f32_e32 v170, v170, v178
	v_add_f32_e32 v170, v170, v198
	v_add_f32_e32 v170, v170, v206
	v_mul_f32_e32 v170, 0x3a800000, v170
	v_add_f32_e32 v170, 0x358637bd, v170
	v_add_f32_e32 v210, v210, v211
	v_add_f32_e32 v212, v212, v213
	v_add_f32_e32 v214, v214, v215
	v_add_f32_e32 v216, v216, v217
	v_add_f32_e32 v218, v218, v219
	v_add_f32_e32 v220, v220, v221
	v_add_f32_e32 v222, v222, v223
	v_add_f32_e32 v224, v224, v225
	v_add_f32_e32 v210, v210, v212
	v_add_f32_e32 v214, v214, v216
	v_add_f32_e32 v218, v218, v220
	v_add_f32_e32 v222, v222, v224
	v_add_f32_e32 v210, v210, v214
	v_add_f32_e32 v210, v210, v218
	v_add_f32_e32 v210, v210, v222
	v_mul_f32_e32 v210, 0x3a800000, v210
	v_add_f32_e32 v210, 0x358637bd, v210
	v_rsq_f32_e32 v128, v128
	v_rsq_f32_e32 v170, v170
	v_rsq_f32_e32 v210, v210
	s_nop 1
	ds_write_b32 v196, v128 offset:768
	ds_write_b32 v196, v170 offset:1024
	ds_write_b32 v196, v210 offset:1280
	v_lshlrev_b32_e32 v226, 6, v156
	v_lshlrev_b32_e32 v227, 6, v154
	global_load_dwordx4 v[128:131], v226, s[2:3]
	global_load_dwordx4 v[132:135], v226, s[2:3] offset:16
	global_load_dwordx4 v[136:139], v226, s[2:3] offset:32
	global_load_dwordx4 v[140:143], v226, s[2:3] offset:48
	global_load_dwordx4 v[170:173], v227, s[2:3]
	global_load_dwordx4 v[178:181], v227, s[2:3] offset:16
	global_load_dwordx4 v[198:201], v227, s[2:3] offset:32
	global_load_dwordx4 v[206:209], v227, s[2:3] offset:48
	s_waitcnt vmcnt(0)
	v_add_f32_e32 v128, v128, v129
	v_add_f32_e32 v130, v130, v131
	v_add_f32_e32 v132, v132, v133
	v_add_f32_e32 v134, v134, v135
	v_add_f32_e32 v136, v136, v137
	v_add_f32_e32 v138, v138, v139
	v_add_f32_e32 v140, v140, v141
	v_add_f32_e32 v142, v142, v143
	v_add_f32_e32 v128, v128, v130
	v_add_f32_e32 v132, v132, v134
	v_add_f32_e32 v136, v136, v138
	v_add_f32_e32 v140, v140, v142
	v_add_f32_e32 v128, v128, v132
	v_add_f32_e32 v128, v128, v136
	v_add_f32_e32 v128, v128, v140
	v_mul_f32_e32 v128, 0x3a800000, v128
	v_add_f32_e32 v128, 0x358637bd, v128
	v_add_f32_e32 v170, v170, v171
	v_add_f32_e32 v172, v172, v173
	v_add_f32_e32 v178, v178, v179
	v_add_f32_e32 v180, v180, v181
	v_add_f32_e32 v198, v198, v199
	v_add_f32_e32 v200, v200, v201
	v_add_f32_e32 v206, v206, v207
	v_add_f32_e32 v208, v208, v209
	v_add_f32_e32 v170, v170, v172
	v_add_f32_e32 v178, v178, v180
	v_add_f32_e32 v198, v198, v200
	v_add_f32_e32 v206, v206, v208
	v_add_f32_e32 v170, v170, v178
	v_add_f32_e32 v170, v170, v198
	v_add_f32_e32 v170, v170, v206
	v_mul_f32_e32 v170, 0x3a800000, v170
	v_add_f32_e32 v170, 0x358637bd, v170
	v_rsq_f32_e32 v128, v128
	v_rsq_f32_e32 v170, v170
	s_nop 1
	ds_write_b32 v196, v128 offset:1536
	ds_write_b32 v196, v170 offset:1792
	s_mov_b64 s[38:39], 0
